# baseline (speedup 1.0000x reference)
; template <int MODE> ...
;     ...
;       const int k32 = kt * 64 + sub * 32;
;       const bool active = (k32 <= w_last) && (w_first < L);
;       SPHASE(sub, active);
.LBB0_329:
	s_add_i32 s2, s78, 32
	v_cmp_le_i32_e32 vcc, s2, v161
	s_and_b64 s[2:3], s[8:9], vcc
	s_and_saveexec_b64 s[14:15], s[2:3]
	s_cbranch_execz .LBB0_331
	ds_read_b128 v[2:5], v162
	ds_read_b128 v[212:215], v163
	ds_read_b128 v[216:219], v164
	ds_read_b128 v[220:223], v165
	ds_read_b128 v[224:227], v166
	ds_read_b128 v[228:231], v167
	ds_read_b128 v[232:235], v168
	ds_read_b128 v[236:239], v169
	s_waitcnt vmcnt(11) lgkmcnt(7)
	v_mfma_f32_32x32x16_bf16 v[80:95], v[2:5], v[96:99], 0
	s_waitcnt vmcnt(10) lgkmcnt(6)
	v_mfma_f32_32x32x16_bf16 v[80:95], v[212:215], v[100:103], v[80:95]
	s_waitcnt vmcnt(9) lgkmcnt(5)
	v_mfma_f32_32x32x16_bf16 v[80:95], v[216:219], v[104:107], v[80:95]
	s_waitcnt vmcnt(8) lgkmcnt(4)
	v_mfma_f32_32x32x16_bf16 v[80:95], v[220:223], v[108:111], v[80:95]
	s_waitcnt vmcnt(7) lgkmcnt(3)
	v_mfma_f32_32x32x16_bf16 v[80:95], v[224:227], v[112:115], v[80:95]
	s_waitcnt vmcnt(6) lgkmcnt(2)
	v_mfma_f32_32x32x16_bf16 v[80:95], v[228:231], v[116:119], v[80:95]
	s_waitcnt vmcnt(5) lgkmcnt(1)
	v_mfma_f32_32x32x16_bf16 v[80:95], v[232:235], v[120:123], v[80:95]
	s_waitcnt vmcnt(4) lgkmcnt(0)
	v_mfma_f32_32x32x16_bf16 v[80:95], v[236:239], v[124:127], v[80:95]

; template <int MODE> ...
;     ...
;       const int k32 = kt * 64 + sub * 32;
;       const bool active = (k32 <= w_last) && (w_first < L);
;       SPHASE(sub, active);
.LBB0_333:
	s_or_b64 exec, exec, s[56:57]
	v_cmp_le_i32_e32 vcc, s78, v161
	s_and_b64 s[2:3], s[8:9], vcc
	s_and_saveexec_b64 s[14:15], s[2:3]
	s_cbranch_execz .LBB0_335
	ds_read_b128 v[2:5], v170
	ds_read_b128 v[212:215], v171
	ds_read_b128 v[216:219], v172
	ds_read_b128 v[220:223], v173
	ds_read_b128 v[224:227], v174
	ds_read_b128 v[228:231], v175
	ds_read_b128 v[232:235], v176
	ds_read_b128 v[236:239], v177
	s_waitcnt vmcnt(11) lgkmcnt(7)
	v_mfma_f32_32x32x16_bf16 v[80:95], v[2:5], v[96:99], 0
	s_waitcnt vmcnt(10) lgkmcnt(6)
	v_mfma_f32_32x32x16_bf16 v[80:95], v[212:215], v[100:103], v[80:95]
	s_waitcnt vmcnt(9) lgkmcnt(5)
	v_mfma_f32_32x32x16_bf16 v[80:95], v[216:219], v[104:107], v[80:95]
	s_waitcnt vmcnt(8) lgkmcnt(4)
	v_mfma_f32_32x32x16_bf16 v[80:95], v[220:223], v[108:111], v[80:95]
	s_waitcnt vmcnt(7) lgkmcnt(3)
	v_mfma_f32_32x32x16_bf16 v[80:95], v[224:227], v[112:115], v[80:95]
	s_waitcnt vmcnt(6) lgkmcnt(2)
	v_mfma_f32_32x32x16_bf16 v[80:95], v[228:231], v[116:119], v[80:95]
	s_waitcnt vmcnt(5) lgkmcnt(1)
	v_mfma_f32_32x32x16_bf16 v[80:95], v[232:235], v[120:123], v[80:95]
	s_waitcnt vmcnt(4) lgkmcnt(0)
	v_mfma_f32_32x32x16_bf16 v[80:95], v[236:239], v[124:127], v[80:95]

; template <int MODE> ...
;     ...
;       const int k32 = kt * 64 + sub * 32;
;       const bool active = (k32 <= w_last) && (w_first < L);
;       SPHASE(sub, active);
.LBB0_350:
	s_sub_i32 s8, s14, 31
	v_cmp_le_i32_e32 vcc, s8, v167
	s_and_b64 s[10:11], s[6:7], vcc
	s_and_saveexec_b64 s[8:9], s[10:11]
	s_cbranch_execz .LBB0_352
	ds_read_b128 v[2:5], v169
	ds_read_b128 v[190:193], v170
	ds_read_b128 v[222:225], v171
	ds_read_b128 v[226:229], v172
	ds_read_b128 v[230:233], v173
	ds_read_b128 v[234:237], v174
	ds_read_b128 v[238:241], v175
	ds_read_b128 v[242:245], v176
	ds_read_b128 v[246:249], v177
	s_waitcnt vmcnt(16) lgkmcnt(8)
	v_mfma_f32_32x32x16_bf16 v[2:17], v[2:5], v[18:21], 0
	s_waitcnt vmcnt(15) lgkmcnt(7)
	v_mfma_f32_32x32x16_bf16 v[2:17], v[190:193], v[22:25], v[2:17]
	ds_read_b128 v[190:193], v178
	s_waitcnt vmcnt(14) lgkmcnt(7)
	v_mfma_f32_32x32x16_bf16 v[2:17], v[222:225], v[26:29], v[2:17]
	ds_read_b128 v[222:225], v179
	s_waitcnt vmcnt(13) lgkmcnt(7)
	v_mfma_f32_32x32x16_bf16 v[2:17], v[226:229], v[96:99], v[2:17]
	ds_read_b128 v[226:229], v203
	s_waitcnt vmcnt(12) lgkmcnt(7)
	v_mfma_f32_32x32x16_bf16 v[2:17], v[230:233], v[100:103], v[2:17]
	s_waitcnt vmcnt(11) lgkmcnt(6)
	v_mfma_f32_32x32x16_bf16 v[2:17], v[234:237], v[104:107], v[2:17]
	s_waitcnt vmcnt(10) lgkmcnt(5)
	v_mfma_f32_32x32x16_bf16 v[2:17], v[238:241], v[108:111], v[2:17]
	s_waitcnt vmcnt(9) lgkmcnt(4)
	v_mfma_f32_32x32x16_bf16 v[2:17], v[242:245], v[112:115], v[2:17]
	s_waitcnt vmcnt(8) lgkmcnt(3)
	v_mfma_f32_32x32x16_bf16 v[2:17], v[246:249], v[116:119], v[2:17]
	s_waitcnt vmcnt(7) lgkmcnt(2)
	v_mfma_f32_32x32x16_bf16 v[2:17], v[190:193], v[120:123], v[2:17]
	s_waitcnt vmcnt(6) lgkmcnt(1)
	v_mfma_f32_32x32x16_bf16 v[2:17], v[222:225], v[124:127], v[2:17]
	s_waitcnt vmcnt(5) lgkmcnt(0)
	v_mfma_f32_32x32x16_bf16 v[2:17], v[226:229], v[128:131], v[2:17]

; template <int MODE> ...
;     ...
;       const int k32 = kt * 64 + sub * 32;
;       const bool active = (k32 <= w_last) && (w_first < L);
;       SPHASE(sub, active);
.LBB0_360:
	s_or_b64 exec, exec, s[8:9]
	s_sub_i32 s8, s14, 63
	v_cmp_le_i32_e32 vcc, s8, v167
	s_and_b64 s[10:11], s[6:7], vcc
	s_and_saveexec_b64 s[8:9], s[10:11]
	s_cbranch_execz .LBB0_362
	s_nop 1
	ds_read_b128 v[2:5], v204
	ds_read_b128 v[190:193], v205
	ds_read_b128 v[222:225], v206
	ds_read_b128 v[226:229], v207
	ds_read_b128 v[230:233], v208
	ds_read_b128 v[234:237], v209
	ds_read_b128 v[238:241], v210
	ds_read_b128 v[242:245], v211
	ds_read_b128 v[246:249], v212
	s_waitcnt vmcnt(16) lgkmcnt(8)
	v_mfma_f32_32x32x16_bf16 v[2:17], v[2:5], v[18:21], 0
	s_waitcnt vmcnt(15) lgkmcnt(7)
	v_mfma_f32_32x32x16_bf16 v[2:17], v[190:193], v[22:25], v[2:17]
	ds_read_b128 v[190:193], v213
	s_waitcnt vmcnt(14) lgkmcnt(7)
	v_mfma_f32_32x32x16_bf16 v[2:17], v[222:225], v[26:29], v[2:17]
	ds_read_b128 v[222:225], v214
	s_waitcnt vmcnt(13) lgkmcnt(7)
	v_mfma_f32_32x32x16_bf16 v[2:17], v[226:229], v[96:99], v[2:17]
	ds_read_b128 v[226:229], v215
	s_waitcnt vmcnt(12) lgkmcnt(7)
	v_mfma_f32_32x32x16_bf16 v[2:17], v[230:233], v[100:103], v[2:17]
	s_waitcnt vmcnt(11) lgkmcnt(6)
	v_mfma_f32_32x32x16_bf16 v[2:17], v[234:237], v[104:107], v[2:17]
	s_waitcnt vmcnt(10) lgkmcnt(5)
	v_mfma_f32_32x32x16_bf16 v[2:17], v[238:241], v[108:111], v[2:17]
	s_waitcnt vmcnt(9) lgkmcnt(4)
	v_mfma_f32_32x32x16_bf16 v[2:17], v[242:245], v[112:115], v[2:17]
	s_waitcnt vmcnt(8) lgkmcnt(3)
	v_mfma_f32_32x32x16_bf16 v[2:17], v[246:249], v[116:119], v[2:17]
	s_waitcnt vmcnt(7) lgkmcnt(2)
	v_mfma_f32_32x32x16_bf16 v[2:17], v[190:193], v[120:123], v[2:17]
	s_waitcnt vmcnt(6) lgkmcnt(1)
	v_mfma_f32_32x32x16_bf16 v[2:17], v[222:225], v[124:127], v[2:17]
	s_waitcnt vmcnt(5) lgkmcnt(0)
	v_mfma_f32_32x32x16_bf16 v[2:17], v[226:229], v[128:131], v[2:17]
